# kt-MFMA version + FFN-out weight transpose (wf2) moved from phase 5 to the workgroups idle in the last gdn_intra round of phase 4
# speedup vs baseline: 1.0018x; 1.0018x over previous
; DI void phase_weights_b(LAS unsigned char* lds, PP p, int l, int bid, int nblk) {
;     ...
;     transpose_job<0>(lds, p->in[25] + (size_t)l * 5632 * 2048, 5632, 2048, (bf16_t*)(ws + O_WF2), bid, nblk);
; __global__ void __launch_bounds__(512, 2) hybrid_fwd(Params p_arg) {
;     ...
;             if (bid < 8) phase_carry(p, bid);
;             else gdn_intra(lds, p, l, bid - 8, G - 8);
;             break;
.LBB0_1186:
	s_cmp_lt_u32 s63, 72
	s_cbranch_scc1 .Lwb4_skip
	v_writelane_b32 v255, s2, 0
	v_writelane_b32 v255, s3, 1
	v_writelane_b32 v255, s20, 2
	v_writelane_b32 v255, s21, 3
	v_writelane_b32 v255, s22, 4
	v_writelane_b32 v255, s23, 5
	v_writelane_b32 v255, s26, 6
	v_writelane_b32 v255, s27, 7
	v_writelane_b32 v255, s28, 8
	v_writelane_b32 v255, s29, 9
	v_writelane_b32 v255, s30, 10
	v_writelane_b32 v255, s31, 11
	v_writelane_b32 v255, s34, 12
	v_writelane_b32 v255, s44, 13
	s_sub_i32 s44, s63, 72
	s_sub_i32 s85, s85, 40
	s_sub_i32 s2, s85, 32
	v_writelane_b32 v254, s2, 8
	s_mov_b32 s2, 2
	v_writelane_b32 v254, s2, 60
	s_waitcnt vmcnt(0) lgkmcnt(0)
	s_barrier
	s_branch .LBB0_213
.Lwb4_ret:
	v_readlane_b32 s44, v255, 13
	s_add_i32 s85, s85, 40
	s_sub_i32 s2, s85, 32
	v_writelane_b32 v254, s2, 8
	s_mov_b32 s2, 0
	v_writelane_b32 v254, s2, 60
	v_readlane_b32 s2, v255, 0
	v_readlane_b32 s3, v255, 1
	v_readlane_b32 s20, v255, 2
	v_readlane_b32 s21, v255, 3
	v_readlane_b32 s22, v255, 4
	v_readlane_b32 s23, v255, 5
	v_readlane_b32 s26, v255, 6
	v_readlane_b32 s27, v255, 7
	v_readlane_b32 s28, v255, 8
	v_readlane_b32 s29, v255, 9
	v_readlane_b32 s30, v255, 10
	v_readlane_b32 s31, v255, 11
	v_readlane_b32 s34, v255, 12
